# stack + QKV rotary table served from LDS (copied once per phase; was 16 serial global-load rounds per unit)
# speedup vs baseline: 1.0328x; 1.0088x over previous
.LBB0_699:
	s_andn2_b64 vcc, exec, s[6:7]
	s_cbranch_vccnz .LBB0_747
	v_ashrrev_i32_e32 v3, 31, v0
	v_lshrrev_b32_e32 v3, 26, v3
	v_lshlrev_b32_e32 v2, 4, v0
	v_add_u32_e32 v3, v0, v3
	v_bfe_i32 v0, v0, 27, 1
	v_lshrrev_b32_e32 v0, 22, v0
	v_add_u32_e32 v0, v2, v0
	v_and_b32_e32 v0, 0xfffffc00, v0
	v_sub_u32_e32 v0, v2, v0
	v_ashrrev_i32_e32 v11, 6, v3
	v_lshrrev_b32_e32 v3, 4, v0
	v_bitop3_b32 v0, v3, v0, 32 bitop3:0x6c
	v_ashrrev_i32_e32 v4, 31, v0
	v_lshrrev_b32_e32 v4, 26, v4
	v_add_u32_e32 v4, v0, v4
	v_readlane_b32 s6, v253, 5
	v_lshlrev_b32_e32 v3, 3, v11
	v_ashrrev_i32_e32 v12, 6, v4
	v_and_b32_e32 v4, 0xc0, v4
	v_readlane_b32 s7, v253, 6
	v_and_b32_e32 v3, -16, v3
	v_sub_u32_e32 v0, v0, v4
	s_and_b64 s[6:7], s[6:7], exec
	v_add_u32_e32 v3, v12, v3
	v_ashrrev_i16_sdwa v0, v245, sext(v0) dst_sel:DWORD dst_unused:UNUSED_PAD src0_sel:DWORD src1_sel:BYTE_0
	v_lshlrev_b32_e32 v5, 5, v11
	v_bfe_i32 v13, v0, 0, 16
	v_lshlrev_b32_e32 v0, 1, v3
	v_lshrrev_b32_e32 v4, 2, v3
	v_and_b32_e32 v6, 3, v12
	s_mov_b32 s6, 0x1fffe0
	v_and_b32_e32 v5, 32, v5
	v_and_b32_e32 v0, 24, v0
	v_and_b32_e32 v4, 4, v4
	v_and_or_b32 v6, v3, s6, v6
	v_or3_b32 v0, v6, v4, v0
	v_add_lshl_u32 v4, v5, v13, 1
	v_add_u32_e32 v2, 0x2000, v2
	v_lshl_add_u32 v134, v3, 11, v4
	v_ashrrev_i32_e32 v3, 31, v2
	v_lshrrev_b32_e32 v3, 22, v3
	v_add_u32_e32 v3, v2, v3
	v_ashrrev_i32_e32 v14, 10, v3
	s_load_dwordx2 s[14:15], s[8:9], 0x88
	v_mul_i32_i24_e32 v3, 0x400, v14
	v_sub_u32_e32 v2, v2, v3
	v_lshrrev_b32_e32 v3, 4, v2
	v_bitop3_b32 v2, v3, v2, 32 bitop3:0x6c
	s_mov_b32 s4, 0x4400000
	v_lshl_add_u32 v0, v0, 11, v4
	v_ashrrev_i32_e32 v4, 31, v2
	s_cselect_b32 s4, s4, 0x4c00000
	s_waitcnt lgkmcnt(0)
	v_mbcnt_lo_u32_b32 v230, -1, 0
	v_mbcnt_hi_u32_b32 v230, -1, v230
	v_add_u32_e32 v230, s92, v230
	v_lshlrev_b32_e32 v230, 4, v230
	global_load_dwordx4 v[232:235], v230, s[14:15]
	v_add_u32_e32 v230, 0x21000, v230
	s_waitcnt vmcnt(0)
	ds_write_b128 v230, v[232:235]
	s_waitcnt lgkmcnt(0)
	s_add_u32 s62, s14, 0x9a00000
	v_lshrrev_b32_e32 v4, 26, v4
	s_addc_u32 s63, s15, 0
	v_lshlrev_b32_e32 v3, 3, v14
	v_add_u32_e32 v4, v2, v4
	s_add_u32 s64, s14, s4
	v_and_b32_e32 v3, -16, v3
	v_ashrrev_i32_e32 v15, 6, v4
	s_addc_u32 s65, s15, 0
	s_ashr_i32 s4, s2, 6
	v_add_u32_e32 v3, v15, v3
	v_and_b32_e32 v4, 0xc0, v4
	v_and_b32_e32 v6, 3, v15
	s_ashr_i32 s35, s34, 31
	s_ashr_i32 s11, s10, 31
	v_sub_u32_e32 v2, v2, v4
	v_and_or_b32 v6, v3, s6, v6
	s_ashr_i32 s6, s2, 8
	s_lshl_b32 s68, s4, 10
	s_lshl_b64 s[8:9], s[34:35], 19
	s_lshl_b64 s[12:13], s[10:11], 19
	v_ashrrev_i16_sdwa v2, v245, sext(v2) dst_sel:DWORD dst_unused:UNUSED_PAD src0_sel:DWORD src1_sel:BYTE_0
	s_add_u32 s36, s64, s12
	v_lshlrev_b32_e32 v5, 5, v14
	v_bfe_i32 v16, v2, 0, 16
	v_lshlrev_b32_e32 v2, 1, v3
	v_lshrrev_b32_e32 v4, 2, v3
	s_addc_u32 s37, s65, s13
	s_add_i32 s69, s68, 0
	v_and_b32_e32 v5, 32, v5
	v_and_b32_e32 v2, 24, v2
	v_and_b32_e32 v4, 4, v4
	s_add_i32 m0, s69, 0x10000
	v_or3_b32 v2, v6, v4, v2
	v_add_lshl_u32 v4, v5, v16, 1
	global_load_lds_dwordx4 v0, s[36:37]
	s_add_i32 m0, s69, 0x12000
	v_lshl_add_u32 v138, v2, 11, v4
	s_add_u32 s12, s36, 0x40000
	global_load_lds_dwordx4 v138, s[36:37]
	s_addc_u32 s13, s37, 0
	s_add_i32 m0, s69, 0x14000
	v_lshl_add_u32 v136, v3, 11, v4
	global_load_lds_dwordx4 v0, s[12:13]
	s_add_i32 m0, s69, 0x16000
	s_add_u32 s30, s62, s8
	s_addc_u32 s31, s63, s9
	s_add_i32 s78, s69, 0x2000
	global_load_lds_dwordx4 v138, s[12:13]
	s_mov_b32 m0, s69
	s_add_u32 s8, s30, 0x40000
	global_load_lds_dwordx4 v134, s[30:31]
	s_mov_b32 m0, s78
	s_addc_u32 s9, s31, 0
	s_add_i32 s79, s69, 0x4000
	global_load_lds_dwordx4 v136, s[30:31]
	s_mov_b32 m0, s79
	s_add_i32 s80, s69, 0x6000
	global_load_lds_dwordx4 v134, s[8:9]
	s_mov_b32 m0, s80
	v_mov_b32_e32 v139, v1
	global_load_lds_dwordx4 v136, s[8:9]
	v_mov_b32_e32 v135, v1
	v_mov_b32_e32 v137, v1
	s_cmp_eq_u32 s6, 1
	v_lshl_add_u64 v[8:9], s[36:37], 0, v[0:1]
	v_lshl_add_u64 v[6:7], s[36:37], 0, v[138:139]
	v_lshl_add_u64 v[2:3], s[30:31], 0, v[134:135]
	s_cselect_b64 s[16:17], -1, 0
	s_cmp_lg_u32 s6, 1
	v_lshl_add_u64 v[4:5], s[30:31], 0, v[136:137]
	s_cbranch_scc1 .LBB0_702
	s_barrier

.LBB0_711:
	s_lshl_b32 s2, s34, 8
	s_lshl_b32 s10, s10, 8
	s_add_i32 s2, s2, s84
	s_or_b32 s30, s10, s85
	s_cmp_lt_i32 s34, 64
	s_cselect_b64 s[34:35], -1, 0
	s_cmp_lt_i32 s30, s81
	s_cselect_b64 s[10:11], -1, 0
	s_and_b64 s[36:37], s[10:11], s[34:35]
	v_cndmask_b32_e64 v130, 0, 1, s[36:37]
	v_cmp_ne_u32_e64 s[10:11], 1, v130
	s_andn2_b64 vcc, exec, s[36:37]
	s_bfe_u32 s13, s2, 0x50006
	v_readlane_b32 s38, v254, 58
	v_readlane_b32 s39, v254, 59
	s_cbranch_vccnz .LBB0_713
	v_and_b32_e32 v131, 64, v249
	v_xor_b32_e32 v130, 32, v249
	v_add_u32_e32 v131, 64, v131
	v_cmp_lt_i32_e32 vcc, v130, v131
	s_nop 1
	v_cndmask_b32_e32 v130, v249, v130, vcc
	v_lshlrev_b32_e32 v130, 2, v130
	ds_bpermute_b32 v168, v130, v126
	ds_bpermute_b32 v170, v130, v122
	ds_bpermute_b32 v169, v130, v127
	ds_bpermute_b32 v171, v130, v123
	ds_bpermute_b32 v155, v130, v128
	ds_bpermute_b32 v174, v130, v124
	ds_bpermute_b32 v175, v130, v129
	ds_bpermute_b32 v176, v130, v125
	v_mov_b32_e32 v130, s13
	v_cndmask_b32_e64 v130, v148, v130, s[6:7]
	v_lshl_or_b32 v164, v130, 7, v154
	v_add_u32_e32 v231, 0x21000, v164
	ds_read_b128 v[130:133], v231 offset:48
	ds_read_b128 v[156:159], v231 offset:32
	ds_read_b128 v[160:163], v231 offset:16
	s_nop 0
	ds_read_b128 v[164:167], v231
	s_waitcnt lgkmcnt(0)
	v_pk_mul_f32 v[168:169], v[142:143], v[168:169]
	v_mul_f32_e32 v155, v142, v155
	s_waitcnt lgkmcnt(0)
	v_mul_f32_e32 v124, v124, v130
	v_mul_f32_e32 v130, v142, v174
	v_mul_f32_e32 v128, v128, v160
	v_mov_b32_e32 v173, v166
	v_mov_b32_e32 v166, v165
	v_mov_b32_e32 v172, v164
	v_pk_mul_f32 v[164:165], v[168:169], v[166:167]
	v_mul_f32_e32 v167, v142, v175
	v_mov_b32_e32 v166, v129
	v_pk_mul_f32 v[162:163], v[166:167], v[162:163]
	v_mul_f32_e32 v160, v155, v161
	v_mov_b32_e32 v129, v162
	v_mov_b32_e32 v161, v163
	v_pk_add_f32 v[128:129], v[128:129], v[160:161]
	v_mov_b32_e32 v161, v158
	v_pk_mul_f32 v[162:163], v[142:143], v[170:171]
	v_mov_b32_e32 v158, v157
	v_mov_b32_e32 v160, v156
	v_pk_mul_f32 v[156:157], v[162:163], v[158:159]
	v_mul_f32_e32 v159, v142, v176
	v_mov_b32_e32 v158, v125
	v_pk_mul_f32 v[132:133], v[158:159], v[132:133]
	v_mul_f32_e32 v130, v130, v131
	v_mov_b32_e32 v125, v132
	v_mov_b32_e32 v131, v133
	v_pk_fma_f32 v[126:127], v[126:127], v[172:173], v[164:165]
	v_pk_fma_f32 v[122:123], v[122:123], v[160:161], v[156:157]
	v_pk_add_f32 v[124:125], v[124:125], v[130:131]
.LBB0_713:
	s_cmpk_lt_i32 s30, 0x400
	s_cselect_b64 vcc, -1, 0
	v_cndmask_b32_e32 v132, 1.0, v251, vcc
	v_or_b32_e32 v155, s2, v148
	v_pk_mul_f32 v[126:127], v[132:133], v[126:127] op_sel_hi:[0,1]
	v_or_b32_e32 v130, s30, v140
	v_pk_mul_f32 v[156:157], v[132:133], v[124:125] op_sel_hi:[0,1]
	v_pk_mul_f32 v[124:125], v[132:133], v[122:123] op_sel_hi:[0,1]
	v_cvt_pk_bf16_f32 v122, v126, v127
	v_mad_i64_i32 v[126:127], s[36:37], v155, s52, 0
	v_ashrrev_i32_e32 v131, 31, v130
	v_pk_mul_f32 v[128:129], v[132:133], v[128:129] op_sel_hi:[0,1]
	v_lshl_add_u64 v[126:127], v[126:127], 1, s[18:19]
	v_cvt_pk_bf16_f32 v123, v128, v129
	v_lshl_add_u64 v[128:129], v[130:131], 1, v[126:127]
	s_and_b64 vcc, exec, s[10:11]
	v_cvt_pk_bf16_f32 v124, v124, v125
	v_cvt_pk_bf16_f32 v125, v156, v157
	global_store_dwordx4 v[128:129], v[122:125], off
	s_cbranch_vccnz .LBB0_715
	s_nop 0
	v_and_b32_e32 v123, 64, v249
	v_xor_b32_e32 v122, 32, v249
	v_add_u32_e32 v123, 64, v123
	v_cmp_lt_i32_e32 vcc, v122, v123
	s_nop 1
	v_cndmask_b32_e32 v122, v249, v122, vcc
	v_lshlrev_b32_e32 v122, 2, v122
	ds_bpermute_b32 v128, v122, v118
	ds_bpermute_b32 v168, v122, v114
	ds_bpermute_b32 v129, v122, v119
	ds_bpermute_b32 v169, v122, v115
	ds_bpermute_b32 v133, v122, v120
	ds_bpermute_b32 v172, v122, v116
	ds_bpermute_b32 v173, v122, v121
	ds_bpermute_b32 v174, v122, v117
	v_mov_b32_e32 v122, s13
	v_cndmask_b32_e64 v122, v150, v122, s[6:7]
	v_lshl_or_b32 v164, v122, 7, v154
	v_add_u32_e32 v231, 0x21000, v164
	ds_read_b128 v[122:125], v231 offset:48
	ds_read_b128 v[156:159], v231 offset:32
	ds_read_b128 v[160:163], v231 offset:16
	s_nop 0
	ds_read_b128 v[164:167], v231
	s_waitcnt lgkmcnt(0)
	v_pk_mul_f32 v[128:129], v[142:143], v[128:129]
	v_mul_f32_e32 v133, v142, v133
	s_waitcnt lgkmcnt(0)
	v_mul_f32_e32 v116, v116, v122
	v_mul_f32_e32 v122, v142, v172
	v_mul_f32_e32 v120, v120, v160
	v_mov_b32_e32 v170, v164
	v_mov_b32_e32 v171, v166
	v_mov_b32_e32 v166, v165
	v_mul_f32_e32 v165, v142, v173
	v_mov_b32_e32 v164, v121
	v_pk_mul_f32 v[162:163], v[164:165], v[162:163]
	v_pk_mul_f32 v[128:129], v[128:129], v[166:167]
	v_mul_f32_e32 v160, v133, v161
	v_mov_b32_e32 v121, v162
	v_mov_b32_e32 v161, v163
	v_pk_fma_f32 v[118:119], v[118:119], v[170:171], v[128:129]
	v_pk_add_f32 v[120:121], v[120:121], v[160:161]
	v_mov_b32_e32 v129, v158
	v_pk_mul_f32 v[160:161], v[142:143], v[168:169]
	v_mov_b32_e32 v158, v157
	v_mov_b32_e32 v128, v156
	v_pk_mul_f32 v[156:157], v[160:161], v[158:159]
	v_mul_f32_e32 v159, v142, v174
	v_mov_b32_e32 v158, v117
	v_pk_mul_f32 v[124:125], v[158:159], v[124:125]
	v_mul_f32_e32 v122, v122, v123
	v_mov_b32_e32 v117, v124
	v_mov_b32_e32 v123, v125
	v_pk_fma_f32 v[114:115], v[114:115], v[128:129], v[156:157]
	v_pk_add_f32 v[116:117], v[116:117], v[122:123]
.LBB0_715:
	v_mov_b32_e32 v133, v132
	v_or_b32_e32 v128, 16, v155
	v_mov_b32_e32 v122, v132
	v_mov_b32_e32 v123, v132
	v_pk_mul_f32 v[118:119], v[132:133], v[118:119]
	v_pk_mul_f32 v[124:125], v[122:123], v[116:117]
	v_pk_mul_f32 v[116:117], v[132:133], v[114:115]
	v_cvt_pk_bf16_f32 v114, v118, v119
	v_mad_i64_i32 v[118:119], s[36:37], v128, s52, 0
	v_pk_mul_f32 v[120:121], v[122:123], v[120:121]
	v_lshl_add_u64 v[118:119], v[118:119], 1, s[18:19]
	v_cvt_pk_bf16_f32 v115, v120, v121
	v_lshl_add_u64 v[120:121], v[130:131], 1, v[118:119]
	s_and_b64 vcc, exec, s[10:11]
	v_cvt_pk_bf16_f32 v116, v116, v117
	v_cvt_pk_bf16_f32 v117, v124, v125
	global_store_dwordx4 v[120:121], v[114:117], off
	s_cbranch_vccnz .LBB0_717
	s_nop 0
	v_and_b32_e32 v115, 64, v249
	v_xor_b32_e32 v114, 32, v249
	v_add_u32_e32 v115, 64, v115
	v_cmp_lt_i32_e32 vcc, v114, v115
	s_nop 1
	v_cndmask_b32_e32 v114, v249, v114, vcc
	v_lshlrev_b32_e32 v114, 2, v114
	ds_bpermute_b32 v120, v114, v110
	ds_bpermute_b32 v124, v114, v106
	ds_bpermute_b32 v121, v114, v111
	ds_bpermute_b32 v125, v114, v107
	ds_bpermute_b32 v168, v114, v112
	ds_bpermute_b32 v169, v114, v108
	ds_bpermute_b32 v170, v114, v113
	ds_bpermute_b32 v171, v114, v109
	v_mov_b32_e32 v114, s13
	v_cndmask_b32_e64 v114, v151, v114, s[6:7]
	v_lshl_or_b32 v128, v114, 7, v154
	v_add_u32_e32 v231, 0x21000, v128
	ds_read_b128 v[114:117], v231 offset:48
	ds_read_b128 v[156:159], v231 offset:32
	ds_read_b128 v[160:163], v231 offset:16
	ds_read_b128 v[164:167], v231
	s_waitcnt lgkmcnt(0)
	v_pk_mul_f32 v[120:121], v[142:143], v[120:121]
	v_pk_mul_f32 v[124:125], v[142:143], v[124:125]
	s_waitcnt lgkmcnt(0)
	v_mul_f32_e32 v108, v108, v114
	v_mul_f32_e32 v114, v142, v169
	v_mul_f32_e32 v112, v112, v160
	v_mov_b32_e32 v129, v166
	v_mov_b32_e32 v166, v165
	v_mov_b32_e32 v128, v164
	v_pk_mul_f32 v[120:121], v[120:121], v[166:167]
	v_mul_f32_e32 v165, v142, v170
	v_mov_b32_e32 v164, v113
	v_pk_fma_f32 v[110:111], v[110:111], v[128:129], v[120:121]
	v_mul_f32_e32 v129, v142, v171
	v_mov_b32_e32 v128, v109
	v_mul_f32_e32 v160, v142, v168
	v_pk_mul_f32 v[162:163], v[164:165], v[162:163]
	v_mov_b32_e32 v121, v158
	v_mov_b32_e32 v158, v157
	v_pk_mul_f32 v[116:117], v[128:129], v[116:117]
	v_mul_f32_e32 v160, v160, v161
	v_mov_b32_e32 v113, v162
	v_mov_b32_e32 v161, v163
	v_mov_b32_e32 v120, v156
	v_pk_mul_f32 v[124:125], v[124:125], v[158:159]
	v_mul_f32_e32 v114, v114, v115
	v_mov_b32_e32 v109, v116
	v_mov_b32_e32 v115, v117
	v_pk_add_f32 v[112:113], v[112:113], v[160:161]
	v_pk_fma_f32 v[106:107], v[106:107], v[120:121], v[124:125]
	v_pk_add_f32 v[108:109], v[108:109], v[114:115]
.LBB0_717:
	s_nop 0
	v_or_b32_e32 v116, 32, v155
	v_pk_mul_f32 v[110:111], v[132:133], v[110:111]
	v_pk_mul_f32 v[114:115], v[122:123], v[108:109]
	v_pk_mul_f32 v[108:109], v[132:133], v[106:107]
	v_cvt_pk_bf16_f32 v106, v110, v111
	v_mad_i64_i32 v[110:111], s[36:37], v116, s52, 0
	v_pk_mul_f32 v[112:113], v[122:123], v[112:113]
	v_lshl_add_u64 v[110:111], v[110:111], 1, s[18:19]
	v_cvt_pk_bf16_f32 v107, v112, v113
	v_lshl_add_u64 v[112:113], v[130:131], 1, v[110:111]
	s_and_b64 vcc, exec, s[10:11]
	v_cvt_pk_bf16_f32 v108, v108, v109
	v_cvt_pk_bf16_f32 v109, v114, v115
	global_store_dwordx4 v[112:113], v[106:109], off
	s_cbranch_vccnz .LBB0_719
	s_nop 0
	v_and_b32_e32 v107, 64, v249
	v_xor_b32_e32 v106, 32, v249
	v_add_u32_e32 v107, 64, v107
	v_cmp_lt_i32_e32 vcc, v106, v107
	s_nop 1
	v_cndmask_b32_e32 v106, v249, v106, vcc
	v_lshlrev_b32_e32 v106, 2, v106
	ds_bpermute_b32 v116, v106, v102
	ds_bpermute_b32 v124, v106, v98
	ds_bpermute_b32 v117, v106, v103
	ds_bpermute_b32 v125, v106, v99
	ds_bpermute_b32 v160, v106, v104
	ds_bpermute_b32 v161, v106, v100
	ds_bpermute_b32 v162, v106, v105
	ds_bpermute_b32 v163, v106, v101
	v_mov_b32_e32 v106, s13
	v_cndmask_b32_e64 v106, v152, v106, s[6:7]
	v_lshl_or_b32 v128, v106, 7, v154
	v_add_u32_e32 v231, 0x21000, v128
	ds_read_b128 v[106:109], v231 offset:48
	ds_read_b128 v[112:115], v231 offset:32
	ds_read_b128 v[120:123], v231 offset:16
	ds_read_b128 v[156:159], v231
	s_waitcnt lgkmcnt(0)
	v_pk_mul_f32 v[116:117], v[142:143], v[116:117]
	s_waitcnt lgkmcnt(0)
	v_mul_f32_e32 v100, v100, v106
	v_mul_f32_e32 v106, v142, v161
	v_mul_f32_e32 v104, v104, v120
	v_mov_b32_e32 v128, v156
	v_mov_b32_e32 v129, v158
	v_mov_b32_e32 v158, v157
	v_mul_f32_e32 v157, v142, v162
	v_mov_b32_e32 v156, v105
	v_mul_f32_e32 v120, v142, v160
	v_pk_mul_f32 v[122:123], v[156:157], v[122:123]
	v_pk_mul_f32 v[116:117], v[116:117], v[158:159]
	v_mul_f32_e32 v120, v120, v121
	v_mov_b32_e32 v105, v122
	v_mov_b32_e32 v121, v123
	v_pk_fma_f32 v[102:103], v[102:103], v[128:129], v[116:117]
	v_pk_add_f32 v[104:105], v[104:105], v[120:121]
	v_mov_b32_e32 v117, v114
	v_pk_mul_f32 v[120:121], v[142:143], v[124:125]
	v_mov_b32_e32 v114, v113
	v_mov_b32_e32 v116, v112
	v_pk_mul_f32 v[112:113], v[120:121], v[114:115]
	v_mul_f32_e32 v115, v142, v163
	v_mov_b32_e32 v114, v101
	v_pk_mul_f32 v[108:109], v[114:115], v[108:109]
	v_mul_f32_e32 v106, v106, v107
	v_mov_b32_e32 v101, v108
	v_mov_b32_e32 v107, v109
	v_pk_fma_f32 v[98:99], v[98:99], v[116:117], v[112:113]
	v_pk_add_f32 v[100:101], v[100:101], v[106:107]
.LBB0_719:
	v_or_b32_e32 v112, 48, v155
	v_mov_b32_e32 v106, v132
	v_mov_b32_e32 v107, v132
	v_pk_mul_f32 v[102:103], v[132:133], v[102:103]
	v_pk_mul_f32 v[108:109], v[106:107], v[100:101]
	v_pk_mul_f32 v[100:101], v[132:133], v[98:99]
	v_cvt_pk_bf16_f32 v98, v102, v103
	v_mad_i64_i32 v[102:103], s[36:37], v112, s52, 0
	v_pk_mul_f32 v[104:105], v[106:107], v[104:105]
	v_lshl_add_u64 v[102:103], v[102:103], 1, s[18:19]
	v_cvt_pk_bf16_f32 v99, v104, v105
	v_cvt_pk_bf16_f32 v100, v100, v101
	v_cvt_pk_bf16_f32 v101, v108, v109
	v_lshl_add_u64 v[104:105], v[130:131], 1, v[102:103]
	v_add_u32_e32 v108, 0x80, v155
	global_store_dwordx4 v[104:105], v[98:101], off
	v_bfe_u32 v105, v108, 6, 5
	s_and_b64 vcc, exec, s[10:11]
	v_cndmask_b32_e64 v98, v148, v105, s[6:7]
	v_lshl_or_b32 v104, v98, 7, v154
	s_cbranch_vccnz .LBB0_721
	v_and_b32_e32 v99, 64, v249
	v_xor_b32_e32 v98, 32, v249
	v_add_u32_e32 v99, 64, v99
	v_cmp_lt_i32_e32 vcc, v98, v99
	s_nop 1
	v_cndmask_b32_e32 v98, v249, v98, vcc
	v_lshlrev_b32_e32 v98, 2, v98
	ds_bpermute_b32 v116, v98, v94
	ds_bpermute_b32 v124, v98, v90
	ds_bpermute_b32 v117, v98, v95
	ds_bpermute_b32 v125, v98, v91
	ds_bpermute_b32 v109, v98, v96
	ds_bpermute_b32 v160, v98, v92
	ds_bpermute_b32 v161, v98, v97
	ds_bpermute_b32 v162, v98, v93
	v_add_u32_e32 v231, 0x21000, v104
	ds_read_b128 v[98:101], v231 offset:48
	ds_read_b128 v[112:115], v231 offset:32
	ds_read_b128 v[120:123], v231 offset:16
	ds_read_b128 v[156:159], v231
	s_waitcnt lgkmcnt(0)
	v_pk_mul_f32 v[116:117], v[142:143], v[116:117]
	v_mul_f32_e32 v109, v142, v109
	s_waitcnt lgkmcnt(0)
	v_mul_f32_e32 v92, v92, v98
	v_mul_f32_e32 v98, v142, v160
	v_mul_f32_e32 v96, v96, v120
	v_mov_b32_e32 v128, v156
	v_mov_b32_e32 v129, v158
	v_mov_b32_e32 v158, v157
	v_mul_f32_e32 v157, v142, v161
	v_mov_b32_e32 v156, v97
	v_pk_mul_f32 v[122:123], v[156:157], v[122:123]
	v_pk_mul_f32 v[116:117], v[116:117], v[158:159]
	v_mul_f32_e32 v120, v109, v121
	v_mov_b32_e32 v97, v122
	v_mov_b32_e32 v121, v123
	v_pk_fma_f32 v[94:95], v[94:95], v[128:129], v[116:117]
	v_pk_add_f32 v[96:97], v[96:97], v[120:121]
	v_mov_b32_e32 v117, v114
	v_pk_mul_f32 v[120:121], v[142:143], v[124:125]
	v_mov_b32_e32 v114, v113
	v_mov_b32_e32 v116, v112
	v_pk_mul_f32 v[112:113], v[120:121], v[114:115]
	v_mul_f32_e32 v115, v142, v162
	v_mov_b32_e32 v114, v93
	v_pk_mul_f32 v[100:101], v[114:115], v[100:101]
	v_mul_f32_e32 v98, v98, v99
	v_mov_b32_e32 v93, v100
	v_mov_b32_e32 v99, v101
	v_pk_fma_f32 v[90:91], v[90:91], v[116:117], v[112:113]
	v_pk_add_f32 v[92:93], v[92:93], v[98:99]
.LBB0_721:
	v_pk_mul_f32 v[94:95], v[132:133], v[94:95]
	v_pk_mul_f32 v[98:99], v[106:107], v[92:93]
	v_pk_mul_f32 v[92:93], v[132:133], v[90:91]
	v_cvt_pk_bf16_f32 v90, v94, v95
	v_mad_i64_i32 v[94:95], s[36:37], v108, s52, 0
	v_pk_mul_f32 v[96:97], v[106:107], v[96:97]
	v_lshl_add_u64 v[94:95], v[94:95], 1, s[18:19]
	v_cvt_pk_bf16_f32 v91, v96, v97
	v_lshl_add_u64 v[96:97], v[130:131], 1, v[94:95]
	v_cvt_pk_bf16_f32 v92, v92, v93
	v_cvt_pk_bf16_f32 v93, v98, v99
	global_store_dwordx4 v[96:97], v[90:93], off
	s_and_b64 vcc, exec, s[10:11]
	s_nop 0
	v_cndmask_b32_e64 v90, v150, v105, s[6:7]
	v_lshl_or_b32 v96, v90, 7, v154
	s_cbranch_vccnz .LBB0_723
	v_and_b32_e32 v91, 64, v249
	v_xor_b32_e32 v90, 32, v249
	v_add_u32_e32 v91, 64, v91
	v_cmp_lt_i32_e32 vcc, v90, v91
	s_nop 1
	v_cndmask_b32_e32 v90, v249, v90, vcc
	v_lshlrev_b32_e32 v90, 2, v90
	ds_bpermute_b32 v116, v90, v86
	ds_bpermute_b32 v120, v90, v82
	ds_bpermute_b32 v117, v90, v87
	ds_bpermute_b32 v121, v90, v83
	ds_bpermute_b32 v97, v90, v88
	ds_bpermute_b32 v124, v90, v84
	ds_bpermute_b32 v125, v90, v89
	ds_bpermute_b32 v128, v90, v85
	v_add_u32_e32 v231, 0x21000, v96
	ds_read_b128 v[90:93], v231 offset:48
	ds_read_b128 v[98:101], v231 offset:32
	ds_read_b128 v[106:109], v231 offset:16
	ds_read_b128 v[112:115], v231
	s_waitcnt lgkmcnt(0)
	v_pk_mul_f32 v[116:117], v[142:143], v[116:117]
	v_mul_f32_e32 v97, v142, v97
	s_waitcnt lgkmcnt(0)
	v_mul_f32_e32 v84, v84, v90
	v_mul_f32_e32 v90, v142, v124
	v_mul_f32_e32 v88, v88, v106
	v_mov_b32_e32 v123, v114
	v_mov_b32_e32 v114, v113
	v_mov_b32_e32 v122, v112
	v_pk_mul_f32 v[112:113], v[116:117], v[114:115]
	v_mul_f32_e32 v115, v142, v125
	v_mov_b32_e32 v114, v89
	v_pk_mul_f32 v[108:109], v[114:115], v[108:109]
	v_mul_f32_e32 v106, v97, v107
	v_mov_b32_e32 v89, v108
	v_mov_b32_e32 v107, v109
	v_pk_add_f32 v[88:89], v[88:89], v[106:107]
	v_mov_b32_e32 v107, v100
	v_pk_mul_f32 v[108:109], v[142:143], v[120:121]
	v_mov_b32_e32 v100, v99
	v_mov_b32_e32 v106, v98
	v_pk_mul_f32 v[98:99], v[108:109], v[100:101]
	v_mul_f32_e32 v101, v142, v128
	v_mov_b32_e32 v100, v85
	v_pk_mul_f32 v[92:93], v[100:101], v[92:93]
	v_mul_f32_e32 v90, v90, v91
	v_mov_b32_e32 v85, v92
	v_mov_b32_e32 v91, v93
	v_pk_fma_f32 v[86:87], v[86:87], v[122:123], v[112:113]
	v_pk_fma_f32 v[82:83], v[82:83], v[106:107], v[98:99]
	v_pk_add_f32 v[84:85], v[84:85], v[90:91]
.LBB0_723:
	v_add_u32_e32 v97, 0x90, v155
	v_mov_b32_e32 v90, v132
	v_mov_b32_e32 v91, v132
	v_pk_mul_f32 v[86:87], v[132:133], v[86:87]
	v_pk_mul_f32 v[92:93], v[90:91], v[84:85]
	v_pk_mul_f32 v[84:85], v[132:133], v[82:83]
	v_cvt_pk_bf16_f32 v82, v86, v87
	v_mad_i64_i32 v[86:87], s[36:37], v97, s52, 0
	v_pk_mul_f32 v[88:89], v[90:91], v[88:89]
	v_lshl_add_u64 v[86:87], v[86:87], 1, s[18:19]
	v_cvt_pk_bf16_f32 v83, v88, v89
	v_lshl_add_u64 v[88:89], v[130:131], 1, v[86:87]
	v_cvt_pk_bf16_f32 v84, v84, v85
	v_cvt_pk_bf16_f32 v85, v92, v93
	global_store_dwordx4 v[88:89], v[82:85], off
	s_and_b64 vcc, exec, s[10:11]
	s_nop 0
	v_cndmask_b32_e64 v82, v151, v105, s[6:7]
	v_lshl_or_b32 v88, v82, 7, v154
	s_cbranch_vccnz .LBB0_725
	v_and_b32_e32 v83, 64, v249
	v_xor_b32_e32 v82, 32, v249
	v_add_u32_e32 v83, 64, v83
	v_cmp_lt_i32_e32 vcc, v82, v83
	s_nop 1
	v_cndmask_b32_e32 v82, v249, v82, vcc
	v_lshlrev_b32_e32 v82, 2, v82
	ds_bpermute_b32 v92, v82, v78
	ds_bpermute_b32 v116, v82, v74
	ds_bpermute_b32 v93, v82, v79
	ds_bpermute_b32 v117, v82, v75
	ds_bpermute_b32 v89, v82, v80
	ds_bpermute_b32 v97, v82, v76
	ds_bpermute_b32 v122, v82, v81
	ds_bpermute_b32 v123, v82, v77
	v_add_u32_e32 v231, 0x21000, v88
	ds_read_b128 v[82:85], v231 offset:48
	ds_read_b128 v[98:101], v231 offset:32
	ds_read_b128 v[106:109], v231 offset:16
	ds_read_b128 v[112:115], v231
	s_waitcnt lgkmcnt(0)
	v_pk_mul_f32 v[92:93], v[142:143], v[92:93]
	v_mul_f32_e32 v89, v142, v89
	s_waitcnt lgkmcnt(0)
	v_mul_f32_e32 v76, v76, v82
	v_mul_f32_e32 v82, v142, v97
	v_mul_f32_e32 v80, v80, v106
	v_mov_b32_e32 v120, v112
	v_mov_b32_e32 v121, v114
	v_mov_b32_e32 v114, v113
	v_mul_f32_e32 v113, v142, v122
	v_mov_b32_e32 v112, v81
	v_pk_mul_f32 v[108:109], v[112:113], v[108:109]
	v_pk_mul_f32 v[92:93], v[92:93], v[114:115]
	v_mul_f32_e32 v106, v89, v107
	v_mov_b32_e32 v81, v108
	v_mov_b32_e32 v107, v109
	v_pk_fma_f32 v[78:79], v[78:79], v[120:121], v[92:93]
	v_pk_add_f32 v[80:81], v[80:81], v[106:107]
	v_mov_b32_e32 v93, v100
	v_pk_mul_f32 v[106:107], v[142:143], v[116:117]
	v_mov_b32_e32 v100, v99
	v_mov_b32_e32 v92, v98
	v_pk_mul_f32 v[98:99], v[106:107], v[100:101]
	v_mul_f32_e32 v101, v142, v123
	v_mov_b32_e32 v100, v77
	v_pk_mul_f32 v[84:85], v[100:101], v[84:85]
	v_mul_f32_e32 v82, v82, v83
	v_mov_b32_e32 v77, v84
	v_mov_b32_e32 v83, v85
	v_pk_fma_f32 v[74:75], v[74:75], v[92:93], v[98:99]
	v_pk_add_f32 v[76:77], v[76:77], v[82:83]
.LBB0_725:
	v_add_u32_e32 v84, 0xa0, v155
	v_pk_mul_f32 v[78:79], v[132:133], v[78:79]
	v_pk_mul_f32 v[82:83], v[90:91], v[76:77]
	v_pk_mul_f32 v[76:77], v[132:133], v[74:75]
	v_cvt_pk_bf16_f32 v74, v78, v79
	v_mad_i64_i32 v[78:79], s[36:37], v84, s52, 0
	v_pk_mul_f32 v[80:81], v[90:91], v[80:81]
	v_lshl_add_u64 v[78:79], v[78:79], 1, s[18:19]
	v_cvt_pk_bf16_f32 v75, v80, v81
	v_lshl_add_u64 v[80:81], v[130:131], 1, v[78:79]
	v_cvt_pk_bf16_f32 v76, v76, v77
	v_cvt_pk_bf16_f32 v77, v82, v83
	global_store_dwordx4 v[80:81], v[74:77], off
	s_and_b64 vcc, exec, s[10:11]
	s_nop 0
	v_cndmask_b32_e64 v74, v152, v105, s[6:7]
	v_lshl_or_b32 v80, v74, 7, v154
	s_cbranch_vccnz .LBB0_727
	v_and_b32_e32 v75, 64, v249
	v_xor_b32_e32 v74, 32, v249
	v_add_u32_e32 v75, 64, v75
	v_cmp_lt_i32_e32 vcc, v74, v75
	s_nop 1
	v_cndmask_b32_e32 v74, v249, v74, vcc
	v_lshlrev_b32_e32 v74, 2, v74
	ds_bpermute_b32 v106, v74, v70
	ds_bpermute_b32 v108, v74, v66
	ds_bpermute_b32 v107, v74, v71
	ds_bpermute_b32 v109, v74, v67
	ds_bpermute_b32 v81, v74, v72
	ds_bpermute_b32 v89, v74, v68
	ds_bpermute_b32 v97, v74, v73
	ds_bpermute_b32 v105, v74, v69
	v_add_u32_e32 v231, 0x21000, v80
	ds_read_b128 v[74:77], v231 offset:48
	ds_read_b128 v[82:85], v231 offset:32
	ds_read_b128 v[90:93], v231 offset:16
	ds_read_b128 v[98:101], v231
	s_waitcnt lgkmcnt(0)
	v_pk_mul_f32 v[106:107], v[142:143], v[106:107]
	v_mul_f32_e32 v81, v142, v81
	s_waitcnt lgkmcnt(0)
	v_mul_f32_e32 v68, v68, v74
	v_mul_f32_e32 v74, v142, v89
	v_mul_f32_e32 v72, v72, v90
	v_mov_b32_e32 v113, v100
	v_mov_b32_e32 v100, v99
	v_mov_b32_e32 v112, v98
	v_pk_mul_f32 v[98:99], v[106:107], v[100:101]
	v_mul_f32_e32 v101, v142, v97
	v_mov_b32_e32 v100, v73
	v_pk_mul_f32 v[92:93], v[100:101], v[92:93]
	v_mul_f32_e32 v90, v81, v91
	v_mov_b32_e32 v73, v92
	v_mov_b32_e32 v91, v93
	v_pk_add_f32 v[72:73], v[72:73], v[90:91]
	v_mov_b32_e32 v91, v84
	v_pk_mul_f32 v[92:93], v[142:143], v[108:109]
	v_mov_b32_e32 v84, v83
	v_mov_b32_e32 v90, v82
	v_pk_mul_f32 v[82:83], v[92:93], v[84:85]
	v_mul_f32_e32 v85, v142, v105
	v_mov_b32_e32 v84, v69
	v_pk_mul_f32 v[76:77], v[84:85], v[76:77]
	v_mul_f32_e32 v74, v74, v75
	v_mov_b32_e32 v69, v76
	v_mov_b32_e32 v75, v77
	v_pk_fma_f32 v[70:71], v[70:71], v[112:113], v[98:99]
	v_pk_fma_f32 v[66:67], v[66:67], v[90:91], v[82:83]
	v_pk_add_f32 v[68:69], v[68:69], v[74:75]
.LBB0_727:
	v_add_u32_e32 v76, 0xb0, v155
	v_mov_b32_e32 v74, v132
	v_mov_b32_e32 v75, v132
	v_pk_mul_f32 v[70:71], v[132:133], v[70:71]
	s_or_b32 s2, s30, 0x80
	v_pk_mul_f32 v[72:73], v[74:75], v[72:73]
	v_pk_mul_f32 v[74:75], v[74:75], v[68:69]
	v_pk_mul_f32 v[68:69], v[132:133], v[66:67]
	v_cvt_pk_bf16_f32 v66, v70, v71
	v_mad_i64_i32 v[70:71], s[10:11], v76, s52, 0
	s_cmp_lt_i32 s2, s81
	s_cselect_b64 s[10:11], -1, 0
	s_and_b64 s[34:35], s[10:11], s[34:35]
	v_cvt_pk_bf16_f32 v67, v72, v73
	v_cvt_pk_bf16_f32 v68, v68, v69
	v_cvt_pk_bf16_f32 v69, v74, v75
	v_lshl_add_u64 v[70:71], v[70:71], 1, s[18:19]
	v_cndmask_b32_e64 v74, 0, 1, s[34:35]
	v_lshl_add_u64 v[72:73], v[130:131], 1, v[70:71]
	v_cmp_ne_u32_e64 s[10:11], 1, v74
	s_andn2_b64 vcc, exec, s[34:35]
	global_store_dwordx4 v[72:73], v[66:69], off
	s_cbranch_vccnz .LBB0_729
	s_nop 0
	v_and_b32_e32 v67, 64, v249
	v_xor_b32_e32 v66, 32, v249
	v_add_u32_e32 v67, 64, v67
	v_cmp_lt_i32_e32 vcc, v66, v67
	s_nop 1
	v_cndmask_b32_e32 v66, v249, v66, vcc
	v_lshlrev_b32_e32 v66, 2, v66
	ds_bpermute_b32 v76, v66, v62
	ds_bpermute_b32 v98, v66, v58
	ds_bpermute_b32 v77, v66, v63
	ds_bpermute_b32 v99, v66, v59
	ds_bpermute_b32 v81, v66, v64
	ds_bpermute_b32 v89, v66, v60
	ds_bpermute_b32 v97, v66, v65
	ds_bpermute_b32 v105, v66, v61
	v_mov_b32_e32 v66, s13
	v_cndmask_b32_e64 v66, v148, v66, s[6:7]
	v_lshl_or_b32 v90, v66, 7, v154
	v_add_u32_e32 v231, 0x21000, v90
	ds_read_b128 v[66:69], v231 offset:48
	ds_read_b128 v[72:75], v231 offset:32
	ds_read_b128 v[82:85], v231 offset:16
	s_nop 0
	ds_read_b128 v[90:93], v231
	s_waitcnt lgkmcnt(0)
	v_pk_mul_f32 v[76:77], v[142:143], v[76:77]
	v_mul_f32_e32 v81, v142, v81
	s_waitcnt lgkmcnt(0)
	v_mul_f32_e32 v60, v60, v66
	v_mul_f32_e32 v66, v142, v89
	v_mul_f32_e32 v64, v64, v82
	v_mov_b32_e32 v100, v90
	v_mov_b32_e32 v101, v92
	v_mov_b32_e32 v92, v91
	v_mul_f32_e32 v91, v142, v97
	v_mov_b32_e32 v90, v65
	v_pk_mul_f32 v[84:85], v[90:91], v[84:85]
	v_pk_mul_f32 v[76:77], v[76:77], v[92:93]
	v_mul_f32_e32 v82, v81, v83
	v_mov_b32_e32 v65, v84
	v_mov_b32_e32 v83, v85
	v_pk_fma_f32 v[62:63], v[62:63], v[100:101], v[76:77]
	v_pk_add_f32 v[64:65], v[64:65], v[82:83]
	v_mov_b32_e32 v77, v74
	v_pk_mul_f32 v[82:83], v[142:143], v[98:99]
	v_mov_b32_e32 v74, v73
	v_mov_b32_e32 v76, v72
	v_pk_mul_f32 v[72:73], v[82:83], v[74:75]
	v_mul_f32_e32 v75, v142, v105
	v_mov_b32_e32 v74, v61
	v_pk_mul_f32 v[68:69], v[74:75], v[68:69]
	v_mul_f32_e32 v66, v66, v67
	v_mov_b32_e32 v61, v68
	v_mov_b32_e32 v67, v69
	v_pk_fma_f32 v[58:59], v[58:59], v[76:77], v[72:73]
	v_pk_add_f32 v[60:61], v[60:61], v[66:67]
.LBB0_729:
	s_cmpk_lt_i32 s2, 0x400
	s_cselect_b64 vcc, -1, 0
	v_cndmask_b32_e32 v66, 1.0, v251, vcc
	v_pk_mul_f32 v[62:63], v[66:67], v[62:63] op_sel_hi:[0,1]
	s_ashr_i32 s31, s30, 31
	v_pk_mul_f32 v[64:65], v[66:67], v[64:65] op_sel_hi:[0,1]
	v_pk_mul_f32 v[68:69], v[66:67], v[60:61] op_sel_hi:[0,1]
	v_pk_mul_f32 v[60:61], v[66:67], v[58:59] op_sel_hi:[0,1]
	v_cvt_pk_bf16_f32 v58, v62, v63
	v_lshl_add_u64 v[62:63], s[30:31], 0, v[140:141]
	v_cvt_pk_bf16_f32 v59, v64, v65
	v_lshl_add_u64 v[64:65], v[62:63], 1, v[126:127]
	s_and_b64 vcc, exec, s[10:11]
	v_cvt_pk_bf16_f32 v60, v60, v61
	v_cvt_pk_bf16_f32 v61, v68, v69
	global_store_dwordx4 v[64:65], v[58:61], off offset:256
	s_cbranch_vccnz .LBB0_731
	s_nop 0
	v_and_b32_e32 v59, 64, v249
	v_xor_b32_e32 v58, 32, v249
	v_add_u32_e32 v59, 64, v59
	v_cmp_lt_i32_e32 vcc, v58, v59
	s_nop 1
	v_cndmask_b32_e32 v58, v249, v58, vcc
	v_lshlrev_b32_e32 v58, 2, v58
	ds_bpermute_b32 v64, v58, v54
	ds_bpermute_b32 v68, v58, v50
	ds_bpermute_b32 v65, v58, v55
	ds_bpermute_b32 v69, v58, v51
	ds_bpermute_b32 v67, v58, v56
	ds_bpermute_b32 v81, v58, v52
	ds_bpermute_b32 v89, v58, v57
	ds_bpermute_b32 v97, v58, v53
	v_mov_b32_e32 v58, s13
	v_cndmask_b32_e64 v58, v150, v58, s[6:7]
	v_lshl_or_b32 v76, v58, 7, v154
	v_add_u32_e32 v231, 0x21000, v76
	ds_read_b128 v[58:61], v231 offset:48
	ds_read_b128 v[72:75], v231 offset:32
	ds_read_b128 v[82:85], v231 offset:16
	ds_read_b128 v[90:93], v231
	s_waitcnt lgkmcnt(0)
	v_pk_mul_f32 v[64:65], v[142:143], v[64:65]
	v_mul_f32_e32 v67, v142, v67
	v_pk_mul_f32 v[68:69], v[142:143], v[68:69]
	s_waitcnt lgkmcnt(0)
	v_mul_f32_e32 v52, v52, v58
	v_mul_f32_e32 v58, v142, v81
	v_mul_f32_e32 v56, v56, v82
	v_mov_b32_e32 v77, v92
	v_mov_b32_e32 v92, v91
	v_mov_b32_e32 v76, v90
	v_pk_mul_f32 v[64:65], v[64:65], v[92:93]
	v_mul_f32_e32 v91, v142, v89
	v_mov_b32_e32 v90, v57
	v_pk_fma_f32 v[54:55], v[54:55], v[76:77], v[64:65]
	v_mov_b32_e32 v64, v72
	v_mov_b32_e32 v65, v74
	v_mov_b32_e32 v74, v73
	v_mul_f32_e32 v73, v142, v97
	v_mov_b32_e32 v72, v53
	v_pk_mul_f32 v[84:85], v[90:91], v[84:85]
	v_pk_mul_f32 v[60:61], v[72:73], v[60:61]
	v_mul_f32_e32 v82, v67, v83
	v_mov_b32_e32 v57, v84
	v_mov_b32_e32 v83, v85
	v_pk_mul_f32 v[68:69], v[68:69], v[74:75]
	v_mul_f32_e32 v58, v58, v59
	v_mov_b32_e32 v53, v60
	v_mov_b32_e32 v59, v61
	v_pk_add_f32 v[56:57], v[56:57], v[82:83]
	v_pk_fma_f32 v[50:51], v[50:51], v[64:65], v[68:69]
	v_pk_add_f32 v[52:53], v[52:53], v[58:59]
.LBB0_731:
	v_mov_b32_e32 v67, v66
	v_mov_b32_e32 v58, v66
	v_mov_b32_e32 v59, v66
	v_pk_mul_f32 v[54:55], v[66:67], v[54:55]
	v_pk_mul_f32 v[60:61], v[58:59], v[52:53]
	v_pk_mul_f32 v[52:53], v[66:67], v[50:51]
	v_cvt_pk_bf16_f32 v50, v54, v55
	v_lshl_add_u64 v[54:55], v[62:63], 1, v[118:119]
	s_and_b64 vcc, exec, s[10:11]
	v_pk_mul_f32 v[56:57], v[58:59], v[56:57]
	s_nop 0
	v_cvt_pk_bf16_f32 v51, v56, v57
	v_cvt_pk_bf16_f32 v52, v52, v53
	v_cvt_pk_bf16_f32 v53, v60, v61
	global_store_dwordx4 v[54:55], v[50:53], off offset:256
	s_cbranch_vccnz .LBB0_733
	s_nop 0
	v_and_b32_e32 v51, 64, v249
	v_xor_b32_e32 v50, 32, v249
	v_add_u32_e32 v51, 64, v51
	v_cmp_lt_i32_e32 vcc, v50, v51
	s_nop 1
	v_cndmask_b32_e32 v50, v249, v50, vcc
	v_lshlrev_b32_e32 v50, 2, v50
	ds_bpermute_b32 v60, v50, v46
	ds_bpermute_b32 v64, v50, v42
	ds_bpermute_b32 v61, v50, v47
	ds_bpermute_b32 v65, v50, v43
	ds_bpermute_b32 v76, v50, v48
	ds_bpermute_b32 v81, v50, v44
	ds_bpermute_b32 v77, v50, v49
	ds_bpermute_b32 v89, v50, v45
	v_mov_b32_e32 v50, s13
	v_cndmask_b32_e64 v50, v151, v50, s[6:7]
	v_lshl_or_b32 v68, v50, 7, v154
	v_add_u32_e32 v231, 0x21000, v68
	ds_read_b128 v[50:53], v231 offset:48
	ds_read_b128 v[54:57], v231 offset:32
	ds_read_b128 v[72:75], v231 offset:16
	ds_read_b128 v[82:85], v231
	s_waitcnt lgkmcnt(0)
	v_pk_mul_f32 v[60:61], v[142:143], v[60:61]
	v_pk_mul_f32 v[64:65], v[142:143], v[64:65]
	v_mul_f32_e32 v77, v142, v77
	s_waitcnt lgkmcnt(0)
	v_mul_f32_e32 v44, v44, v50
	v_mul_f32_e32 v50, v142, v81
	v_mul_f32_e32 v48, v48, v72
	v_mov_b32_e32 v69, v84
	v_mov_b32_e32 v84, v83
	v_mov_b32_e32 v68, v82
	v_pk_mul_f32 v[60:61], v[60:61], v[84:85]
	v_mul_f32_e32 v72, v142, v76
	v_pk_fma_f32 v[46:47], v[46:47], v[68:69], v[60:61]
	v_mov_b32_e32 v61, v56
	v_mov_b32_e32 v56, v55
	v_mov_b32_e32 v76, v49
	v_mov_b32_e32 v60, v54
	v_pk_mul_f32 v[54:55], v[64:65], v[56:57]
	v_mul_f32_e32 v57, v142, v89
	v_mov_b32_e32 v56, v45
	v_pk_mul_f32 v[74:75], v[76:77], v[74:75]
	v_pk_mul_f32 v[52:53], v[56:57], v[52:53]
	v_mul_f32_e32 v72, v72, v73
	v_mov_b32_e32 v49, v74
	v_mov_b32_e32 v73, v75
	v_mul_f32_e32 v50, v50, v51
	v_mov_b32_e32 v45, v52
	v_mov_b32_e32 v51, v53
	v_pk_add_f32 v[48:49], v[48:49], v[72:73]
	v_pk_fma_f32 v[42:43], v[42:43], v[60:61], v[54:55]
	v_pk_add_f32 v[44:45], v[44:45], v[50:51]
.LBB0_733:
	v_pk_mul_f32 v[46:47], v[66:67], v[46:47]
	v_pk_mul_f32 v[50:51], v[58:59], v[44:45]
	v_pk_mul_f32 v[44:45], v[66:67], v[42:43]
	v_cvt_pk_bf16_f32 v42, v46, v47
	v_lshl_add_u64 v[46:47], v[62:63], 1, v[110:111]
	s_and_b64 vcc, exec, s[10:11]
	v_pk_mul_f32 v[48:49], v[58:59], v[48:49]
	s_nop 0
	v_cvt_pk_bf16_f32 v43, v48, v49
	v_cvt_pk_bf16_f32 v44, v44, v45
	v_cvt_pk_bf16_f32 v45, v50, v51
	global_store_dwordx4 v[46:47], v[42:45], off offset:256
	s_cbranch_vccnz .LBB0_735
	s_nop 0
	v_mov_b32_e32 v42, s13
	v_cndmask_b32_e64 v42, v152, v42, s[6:7]
	v_lshl_or_b32 v54, v42, 7, v154
	v_add_u32_e32 v231, 0x21000, v54
	ds_read_b128 v[42:45], v231
	ds_read_b128 v[46:49], v231 offset:16
	ds_read_b128 v[50:53], v231 offset:32
	s_nop 0
	ds_read_b128 v[54:57], v231 offset:48
	v_and_b32_e32 v61, 64, v249
	v_xor_b32_e32 v59, 32, v249
	v_add_u32_e32 v61, 64, v61
	v_cmp_lt_i32_e32 vcc, v59, v61
	v_mov_b32_e32 v58, v41
	v_mov_b32_e32 v60, v37
	v_cndmask_b32_e32 v59, v249, v59, vcc
	v_lshlrev_b32_e32 v59, 2, v59
	ds_bpermute_b32 v61, v59, v40
	ds_bpermute_b32 v41, v59, v41
	ds_bpermute_b32 v72, v59, v36
	ds_bpermute_b32 v37, v59, v37
	ds_bpermute_b32 v64, v59, v38
	ds_bpermute_b32 v68, v59, v34
	ds_bpermute_b32 v65, v59, v39
	ds_bpermute_b32 v69, v59, v35
	s_waitcnt lgkmcnt(0)
	v_mul_f32_e32 v74, v142, v61
	v_mul_f32_e32 v59, v142, v41
	v_mul_f32_e32 v41, v142, v72
	v_mul_f32_e32 v61, v142, v37
	v_pk_mul_f32 v[64:65], v[142:143], v[64:65]
	v_pk_mul_f32 v[68:69], v[142:143], v[68:69]
	s_waitcnt lgkmcnt(0)
	v_mov_b32_e32 v72, v42
	v_mov_b32_e32 v73, v44
	v_mov_b32_e32 v44, v43
	v_mul_f32_e32 v40, v40, v46
	v_mul_f32_e32 v42, v74, v47
	v_pk_mul_f32 v[46:47], v[58:59], v[48:49]
	v_mov_b32_e32 v48, v50
	v_mov_b32_e32 v49, v52
	v_mov_b32_e32 v52, v51
	v_mul_f32_e32 v36, v36, v54
	v_mul_f32_e32 v50, v41, v55
	v_pk_mul_f32 v[54:55], v[60:61], v[56:57]
	v_pk_mul_f32 v[44:45], v[64:65], v[44:45]
	v_mov_b32_e32 v41, v46
	v_mov_b32_e32 v43, v47
	v_pk_mul_f32 v[46:47], v[68:69], v[52:53]
	v_mov_b32_e32 v37, v54
	v_mov_b32_e32 v51, v55
	v_pk_fma_f32 v[38:39], v[38:39], v[72:73], v[44:45]
	v_pk_add_f32 v[40:41], v[40:41], v[42:43]
	v_pk_fma_f32 v[34:35], v[34:35], v[48:49], v[46:47]
	v_pk_add_f32 v[36:37], v[36:37], v[50:51]
.LBB0_735:
	s_nop 0
	v_mov_b32_e32 v42, v66
	v_mov_b32_e32 v43, v66
	v_pk_mul_f32 v[38:39], v[66:67], v[38:39]
	v_pk_mul_f32 v[44:45], v[42:43], v[36:37]
	v_pk_mul_f32 v[36:37], v[66:67], v[34:35]
	v_cvt_pk_bf16_f32 v34, v38, v39
	v_lshl_add_u64 v[38:39], v[62:63], 1, v[102:103]
	s_and_b64 vcc, exec, s[10:11]
	v_pk_mul_f32 v[40:41], v[42:43], v[40:41]
	s_nop 0
	v_cvt_pk_bf16_f32 v35, v40, v41
	v_cvt_pk_bf16_f32 v36, v36, v37
	v_cvt_pk_bf16_f32 v37, v44, v45
	global_store_dwordx4 v[38:39], v[34:37], off offset:256
	s_cbranch_vccnz .LBB0_737
	s_nop 0
	v_and_b32_e32 v35, 64, v249
	v_xor_b32_e32 v34, 32, v249
	v_add_u32_e32 v35, 64, v35
	v_cmp_lt_i32_e32 vcc, v34, v35
	s_nop 1
	v_cndmask_b32_e32 v34, v249, v34, vcc
	v_lshlrev_b32_e32 v34, 2, v34
	ds_bpermute_b32 v52, v34, v30
	ds_bpermute_b32 v54, v34, v26
	ds_bpermute_b32 v53, v34, v31
	ds_bpermute_b32 v55, v34, v27
	ds_bpermute_b32 v58, v34, v32
	ds_bpermute_b32 v59, v34, v28
	ds_bpermute_b32 v60, v34, v33
	ds_bpermute_b32 v61, v34, v29
	v_add_u32_e32 v231, 0x21000, v104
	ds_read_b128 v[34:37], v231 offset:48
	ds_read_b128 v[38:41], v231 offset:32
	ds_read_b128 v[44:47], v231 offset:16
	ds_read_b128 v[48:51], v231
	s_waitcnt lgkmcnt(0)
	v_pk_mul_f32 v[52:53], v[142:143], v[52:53]
	s_waitcnt lgkmcnt(0)
	v_mul_f32_e32 v28, v28, v34
	v_mul_f32_e32 v34, v142, v59
	v_mul_f32_e32 v32, v32, v44
	v_mov_b32_e32 v57, v50
	v_mov_b32_e32 v50, v49
	v_mov_b32_e32 v56, v48
	v_pk_mul_f32 v[48:49], v[52:53], v[50:51]
	v_mul_f32_e32 v51, v142, v60
	v_mov_b32_e32 v50, v33
	v_mul_f32_e32 v44, v142, v58
	v_pk_mul_f32 v[46:47], v[50:51], v[46:47]
	v_mul_f32_e32 v44, v44, v45
	v_mov_b32_e32 v33, v46
	v_mov_b32_e32 v45, v47
	v_pk_add_f32 v[32:33], v[32:33], v[44:45]
	v_mov_b32_e32 v45, v40
	v_pk_mul_f32 v[46:47], v[142:143], v[54:55]
	v_mov_b32_e32 v40, v39
	v_mov_b32_e32 v44, v38
	v_pk_mul_f32 v[38:39], v[46:47], v[40:41]
	v_mul_f32_e32 v41, v142, v61
	v_mov_b32_e32 v40, v29
	v_pk_mul_f32 v[36:37], v[40:41], v[36:37]
	v_mul_f32_e32 v34, v34, v35
	v_mov_b32_e32 v29, v36
	v_mov_b32_e32 v35, v37
	v_pk_fma_f32 v[30:31], v[30:31], v[56:57], v[48:49]
	v_pk_fma_f32 v[26:27], v[26:27], v[44:45], v[38:39]
	v_pk_add_f32 v[28:29], v[28:29], v[34:35]
.LBB0_737:
	v_pk_mul_f32 v[30:31], v[66:67], v[30:31]
	v_pk_mul_f32 v[34:35], v[42:43], v[28:29]
	v_pk_mul_f32 v[28:29], v[66:67], v[26:27]
	v_cvt_pk_bf16_f32 v26, v30, v31
	v_lshl_add_u64 v[30:31], v[62:63], 1, v[94:95]
	s_and_b64 vcc, exec, s[10:11]
	v_pk_mul_f32 v[32:33], v[42:43], v[32:33]
	s_nop 0
	v_cvt_pk_bf16_f32 v27, v32, v33
	v_cvt_pk_bf16_f32 v28, v28, v29
	v_cvt_pk_bf16_f32 v29, v34, v35
	global_store_dwordx4 v[30:31], v[26:29], off offset:256
	s_cbranch_vccnz .LBB0_739
	s_nop 0
	v_and_b32_e32 v27, 64, v249
	v_xor_b32_e32 v26, 32, v249
	v_add_u32_e32 v27, 64, v27
	v_cmp_lt_i32_e32 vcc, v26, v27
	s_nop 1
	v_cndmask_b32_e32 v26, v249, v26, vcc
	v_lshlrev_b32_e32 v26, 2, v26
	ds_bpermute_b32 v42, v26, v22
	ds_bpermute_b32 v44, v26, v18
	ds_bpermute_b32 v43, v26, v23
	ds_bpermute_b32 v45, v26, v19
	ds_bpermute_b32 v48, v26, v24
	ds_bpermute_b32 v49, v26, v20
	ds_bpermute_b32 v50, v26, v25
	ds_bpermute_b32 v51, v26, v21
	v_add_u32_e32 v231, 0x21000, v96
	ds_read_b128 v[26:29], v231 offset:48
	ds_read_b128 v[30:33], v231 offset:32
	ds_read_b128 v[34:37], v231 offset:16
	ds_read_b128 v[38:41], v231
	s_waitcnt lgkmcnt(0)
	v_pk_mul_f32 v[42:43], v[142:143], v[42:43]
	s_waitcnt lgkmcnt(0)
	v_mul_f32_e32 v20, v20, v26
	v_mul_f32_e32 v26, v142, v49
	v_mul_f32_e32 v24, v24, v34
	v_mov_b32_e32 v47, v40
	v_mov_b32_e32 v40, v39
	v_mov_b32_e32 v46, v38
	v_pk_mul_f32 v[38:39], v[42:43], v[40:41]
	v_mul_f32_e32 v41, v142, v50
	v_mov_b32_e32 v40, v25
	v_mul_f32_e32 v34, v142, v48
	v_pk_mul_f32 v[36:37], v[40:41], v[36:37]
	v_mul_f32_e32 v34, v34, v35
	v_mov_b32_e32 v25, v36
	v_mov_b32_e32 v35, v37
	v_pk_add_f32 v[24:25], v[24:25], v[34:35]
	v_mov_b32_e32 v35, v32
	v_pk_mul_f32 v[36:37], v[142:143], v[44:45]
	v_mov_b32_e32 v32, v31
	v_mov_b32_e32 v34, v30
	v_pk_mul_f32 v[30:31], v[36:37], v[32:33]
	v_mul_f32_e32 v33, v142, v51
	v_mov_b32_e32 v32, v21
	v_pk_mul_f32 v[28:29], v[32:33], v[28:29]
	v_mul_f32_e32 v26, v26, v27
	v_mov_b32_e32 v21, v28
	v_mov_b32_e32 v27, v29
	v_pk_fma_f32 v[22:23], v[22:23], v[46:47], v[38:39]
	v_pk_fma_f32 v[18:19], v[18:19], v[34:35], v[30:31]
	v_pk_add_f32 v[20:21], v[20:21], v[26:27]
.LBB0_739:
	s_nop 0
	v_mov_b32_e32 v26, v66
	v_mov_b32_e32 v27, v66
	v_pk_mul_f32 v[22:23], v[66:67], v[22:23]
	v_pk_mul_f32 v[28:29], v[26:27], v[20:21]
	v_pk_mul_f32 v[20:21], v[66:67], v[18:19]
	v_cvt_pk_bf16_f32 v18, v22, v23
	v_lshl_add_u64 v[22:23], v[62:63], 1, v[86:87]
	s_and_b64 vcc, exec, s[10:11]
	v_pk_mul_f32 v[24:25], v[26:27], v[24:25]
	s_nop 0
	v_cvt_pk_bf16_f32 v19, v24, v25
	v_cvt_pk_bf16_f32 v20, v20, v21
	v_cvt_pk_bf16_f32 v21, v28, v29
	global_store_dwordx4 v[22:23], v[18:21], off offset:256
	s_cbranch_vccnz .LBB0_741
	s_nop 0
	v_and_b32_e32 v19, 64, v249
	v_xor_b32_e32 v18, 32, v249
	v_add_u32_e32 v19, 64, v19
	v_cmp_lt_i32_e32 vcc, v18, v19
	s_nop 1
	v_cndmask_b32_e32 v18, v249, v18, vcc
	v_lshlrev_b32_e32 v18, 2, v18
	ds_bpermute_b32 v36, v18, v14
	ds_bpermute_b32 v38, v18, v10
	ds_bpermute_b32 v37, v18, v15
	ds_bpermute_b32 v39, v18, v11
	ds_bpermute_b32 v42, v18, v16
	ds_bpermute_b32 v43, v18, v12
	ds_bpermute_b32 v44, v18, v17
	ds_bpermute_b32 v45, v18, v13
	v_add_u32_e32 v231, 0x21000, v88
	ds_read_b128 v[18:21], v231 offset:48
	ds_read_b128 v[22:25], v231 offset:32
	ds_read_b128 v[28:31], v231 offset:16
	ds_read_b128 v[32:35], v231
	s_waitcnt lgkmcnt(0)
	v_pk_mul_f32 v[36:37], v[142:143], v[36:37]
	s_waitcnt lgkmcnt(0)
	v_mul_f32_e32 v12, v12, v18
	v_mul_f32_e32 v18, v142, v43
	v_mul_f32_e32 v16, v16, v28
	v_mov_b32_e32 v41, v34
	v_mov_b32_e32 v34, v33
	v_mov_b32_e32 v40, v32
	v_pk_mul_f32 v[32:33], v[36:37], v[34:35]
	v_mul_f32_e32 v35, v142, v44
	v_mov_b32_e32 v34, v17
	v_mul_f32_e32 v28, v142, v42
	v_pk_mul_f32 v[30:31], v[34:35], v[30:31]
	v_mul_f32_e32 v28, v28, v29
	v_mov_b32_e32 v17, v30
	v_mov_b32_e32 v29, v31
	v_pk_add_f32 v[16:17], v[16:17], v[28:29]
	v_mov_b32_e32 v29, v24
	v_pk_mul_f32 v[30:31], v[142:143], v[38:39]
	v_mov_b32_e32 v24, v23
	v_mov_b32_e32 v28, v22
	v_pk_mul_f32 v[22:23], v[30:31], v[24:25]
	v_mul_f32_e32 v25, v142, v45
	v_mov_b32_e32 v24, v13
	v_pk_mul_f32 v[20:21], v[24:25], v[20:21]
	v_mul_f32_e32 v18, v18, v19
	v_mov_b32_e32 v13, v20
	v_mov_b32_e32 v19, v21
	v_pk_fma_f32 v[14:15], v[14:15], v[40:41], v[32:33]
	v_pk_fma_f32 v[10:11], v[10:11], v[28:29], v[22:23]
	v_pk_add_f32 v[12:13], v[12:13], v[18:19]
.LBB0_741:
	v_pk_mul_f32 v[14:15], v[66:67], v[14:15]
	v_pk_mul_f32 v[18:19], v[26:27], v[12:13]
	v_pk_mul_f32 v[12:13], v[66:67], v[10:11]
	v_cvt_pk_bf16_f32 v10, v14, v15
	v_lshl_add_u64 v[14:15], v[62:63], 1, v[78:79]
	s_and_b64 vcc, exec, s[10:11]
	v_pk_mul_f32 v[16:17], v[26:27], v[16:17]
	s_nop 0
	v_cvt_pk_bf16_f32 v11, v16, v17
	v_cvt_pk_bf16_f32 v12, v12, v13
	v_cvt_pk_bf16_f32 v13, v18, v19
	global_store_dwordx4 v[14:15], v[10:13], off offset:256
	s_cbranch_vccnz .LBB0_743
	s_nop 0
	v_and_b32_e32 v11, 64, v249
	v_xor_b32_e32 v10, 32, v249
	v_add_u32_e32 v11, 64, v11
	v_cmp_lt_i32_e32 vcc, v10, v11
	s_nop 1
	v_cndmask_b32_e32 v10, v249, v10, vcc
	v_lshlrev_b32_e32 v10, 2, v10
	ds_bpermute_b32 v26, v10, v6
	ds_bpermute_b32 v28, v10, v2
	ds_bpermute_b32 v27, v10, v7
	ds_bpermute_b32 v29, v10, v3
	ds_bpermute_b32 v32, v10, v8
	ds_bpermute_b32 v33, v10, v4
	ds_bpermute_b32 v34, v10, v9
	ds_bpermute_b32 v35, v10, v5
	v_add_u32_e32 v231, 0x21000, v80
	ds_read_b128 v[10:13], v231 offset:48
	ds_read_b128 v[14:17], v231 offset:32
	ds_read_b128 v[18:21], v231 offset:16
	ds_read_b128 v[22:25], v231
	s_waitcnt lgkmcnt(0)
	v_pk_mul_f32 v[26:27], v[142:143], v[26:27]
	s_waitcnt lgkmcnt(0)
	v_mul_f32_e32 v4, v4, v10
	v_mul_f32_e32 v10, v142, v33
	v_mul_f32_e32 v8, v8, v18
	v_mov_b32_e32 v31, v24
	v_mov_b32_e32 v24, v23
	v_mov_b32_e32 v30, v22
	v_pk_mul_f32 v[22:23], v[26:27], v[24:25]
	v_mul_f32_e32 v25, v142, v34
	v_mov_b32_e32 v24, v9
	v_mul_f32_e32 v18, v142, v32
	v_pk_mul_f32 v[20:21], v[24:25], v[20:21]
	v_mul_f32_e32 v18, v18, v19
	v_mov_b32_e32 v9, v20
	v_mov_b32_e32 v19, v21
	v_pk_add_f32 v[8:9], v[8:9], v[18:19]
	v_mov_b32_e32 v19, v16
	v_pk_mul_f32 v[20:21], v[142:143], v[28:29]
	v_mov_b32_e32 v16, v15
	v_mov_b32_e32 v18, v14
	v_pk_mul_f32 v[14:15], v[20:21], v[16:17]
	v_mul_f32_e32 v17, v142, v35
	v_mov_b32_e32 v16, v5
	v_pk_mul_f32 v[12:13], v[16:17], v[12:13]
	v_mul_f32_e32 v10, v10, v11
	v_mov_b32_e32 v5, v12
	v_mov_b32_e32 v11, v13
	v_pk_fma_f32 v[6:7], v[6:7], v[30:31], v[22:23]
	v_pk_fma_f32 v[2:3], v[2:3], v[18:19], v[14:15]
	v_pk_add_f32 v[4:5], v[4:5], v[10:11]
